# C1 + mLSTM chunk-state path moved in 16-byte pieces: phase A stores U as dwordx4 (two d-tiles per lane), phase C loads its C fragments as dwordx4 (new element order inside a unit, scan phase unchanged
# speedup vs baseline: 1.0007x; 1.0007x over previous
; __device__ __forceinline__ unsigned pk2(float lo, float hi) { const hwf2 v = {lo, hi}; return __builtin_bit_cast(unsigned, __builtin_convertvector(v, hwbf2)); }
; #define MFMA16(a, b, c) __builtin_amdgcn_mfma_f32_16x16x32_bf16((a), (b), (c), 0, 0, 0)
; __device__ __forceinline__ void mlstm_u_unit(const KP& p, int b, int n, int h, LAS unsigned char* lds, MuPre& pre, PoolPre& ppre) {
;     ...
;       u32x2* um = (u32x2*)GP(bf16_t, WS_UM) + (size_t)ug * 16384 + lane;
; #pragma unroll 4
;       for (int jt = 0; jt < 16; ++jt) { const bf16x8 b0 = tr_frag(Vw, 264, 8 * g4, 8 * g4 + 4, 16 * jt, lane), b1 = tr_frag(Vw, 264, 32 + 8 * g4, 36 + 8 * g4, 16 * jt, lane);
; #pragma unroll
;           for (int d2 = 0; d2 < 2; ++d2) { f32x4 acc = MFMA16(a[d2][0], b0, F4ZERO); acc = MFMA16(a[d2][1], b1, acc); u32x2 w; w.x = pk2(acc[0], acc[1]); w.y = pk2(acc[2], acc[3]); um[((2 * wave + d2) * 16 + jt) * 64] = w; } } }
;     if (tid < 256) { float s = 0.f;
.LBB0_1189:
	v_add_u32_e32 v35, s5, v3
	ds_read_b64_tr_b16 v[80:81], v35 offset:33792
	ds_read_b64_tr_b16 v[82:83], v35 offset:35904
	ds_read_b64_tr_b16 v[84:85], v35 offset:50688
	ds_read_b64_tr_b16 v[86:87], v35 offset:52800
	v_lshl_add_u64 v[38:39], v[4:5], 1, s[16:17]
	s_addk_i32 s5, 0x80
	s_waitcnt lgkmcnt(2)
	v_mfma_f32_16x16x32_bf16 v[88:91], v[64:67], v[80:83], 0
	v_mfma_f32_16x16x32_bf16 v[80:83], v[68:71], v[80:83], 0
	s_waitcnt lgkmcnt(0)
	v_mfma_f32_16x16x32_bf16 v[88:91], v[72:75], v[84:87], v[88:91]
	v_mfma_f32_16x16x32_bf16 v[80:83], v[76:79], v[84:87], v[80:83]
	s_nop 7
	v_cvt_pk_bf16_f32 v240, v88, v89
	v_cvt_pk_bf16_f32 v241, v90, v91
	v_cvt_pk_bf16_f32 v242, v80, v81
	v_cvt_pk_bf16_f32 v243, v82, v83
	global_store_dwordx4 v[38:39], v[240:243], off
	ds_read_b64_tr_b16 v[82:83], v35 offset:33824
	ds_read_b64_tr_b16 v[84:85], v35 offset:35936
	ds_read_b64_tr_b16 v[86:87], v35 offset:50720
	ds_read_b64_tr_b16 v[88:89], v35 offset:52832
	s_waitcnt lgkmcnt(2)
	v_mfma_f32_16x16x32_bf16 v[90:93], v[64:67], v[82:85], 0
	v_mfma_f32_16x16x32_bf16 v[82:85], v[68:71], v[82:85], 0
	s_waitcnt lgkmcnt(0)
	v_mfma_f32_16x16x32_bf16 v[90:93], v[72:75], v[86:89], v[90:93]
	v_mfma_f32_16x16x32_bf16 v[82:85], v[76:79], v[86:89], v[82:85]
	s_nop 7
	v_cvt_pk_bf16_f32 v240, v90, v91
	v_cvt_pk_bf16_f32 v241, v92, v93
	v_cvt_pk_bf16_f32 v242, v82, v83
	v_cvt_pk_bf16_f32 v243, v84, v85
	global_store_dwordx4 v[38:39], v[240:243], off offset:1024
	ds_read_b64_tr_b16 v[82:83], v35 offset:33856
	ds_read_b64_tr_b16 v[84:85], v35 offset:35968
	ds_read_b64_tr_b16 v[86:87], v35 offset:50752
	ds_read_b64_tr_b16 v[88:89], v35 offset:52864
	s_waitcnt lgkmcnt(2)
	v_mfma_f32_16x16x32_bf16 v[90:93], v[64:67], v[82:85], 0
	v_mfma_f32_16x16x32_bf16 v[82:85], v[68:71], v[82:85], 0
	s_waitcnt lgkmcnt(0)
	v_mfma_f32_16x16x32_bf16 v[90:93], v[72:75], v[86:89], v[90:93]
	v_mfma_f32_16x16x32_bf16 v[82:85], v[76:79], v[86:89], v[82:85]
	s_nop 7
	v_cvt_pk_bf16_f32 v240, v90, v91
	v_cvt_pk_bf16_f32 v241, v92, v93
	v_cvt_pk_bf16_f32 v242, v82, v83
	v_cvt_pk_bf16_f32 v243, v84, v85
	global_store_dwordx4 v[38:39], v[240:243], off offset:2048
	ds_read_b64_tr_b16 v[82:83], v35 offset:33888
	ds_read_b64_tr_b16 v[84:85], v35 offset:36000
	ds_read_b64_tr_b16 v[86:87], v35 offset:50784
	ds_read_b64_tr_b16 v[88:89], v35 offset:52896
	s_waitcnt lgkmcnt(2)
	v_mfma_f32_16x16x32_bf16 v[90:93], v[64:67], v[82:85], 0
	v_mfma_f32_16x16x32_bf16 v[82:85], v[68:71], v[82:85], 0
	s_waitcnt lgkmcnt(0)
	v_mfma_f32_16x16x32_bf16 v[90:93], v[72:75], v[86:89], v[90:93]
	v_mfma_f32_16x16x32_bf16 v[82:85], v[76:79], v[86:89], v[82:85]
	s_nop 7
	v_cvt_pk_bf16_f32 v240, v90, v91
	v_cvt_pk_bf16_f32 v241, v92, v93
	v_cvt_pk_bf16_f32 v242, v82, v83
	v_cvt_pk_bf16_f32 v243, v84, v85
	global_store_dwordx4 v[38:39], v[240:243], off offset:3072
	s_add_u32 s16, s16, 0x1000
	s_addc_u32 s17, s17, 0
	s_cmpk_eq_i32 s5, 0x200
	s_cbranch_scc0 .LBB0_1189
	s_movk_i32 s0, 0x100
	v_cmp_gt_i32_e32 vcc, s0, v34
	s_and_saveexec_b64 s[0:1], vcc
	s_cbranch_execz .LBB0_1194
	v_lshlrev_b32_e32 v4, 1, v34
	v_mov_b32_e32 v3, 0
	s_movk_i32 s5, 0xff00

; __device__ __forceinline__ float logsigmoid_f(float x) { return fminf(x, 0.0f) - __logf(1.0f + __expf(-fabsf(x))); }
; __device__ __forceinline__ void mlstm_out_unit(const KP& p, int j, int b, int n, int h, LAS unsigned char* lds, TilesML& pre, bool has_next, int b2, int n2, int h2) {
;     ...
;     u32x2 cf[2][16];
;     { const u32x2* CS = (const u32x2*)GP(const bf16_t, WS_CS) + (size_t)ug * 16384 + lane;
; #pragma unroll
;       for (int j2 = 0; j2 < 2; ++j2)
; #pragma unroll
;           for (int dt = 0; dt < 16; ++dt) cf[j2][dt] = CS[(dt * 16 + 2 * wave + j2) * 64]; }
;     if (wave == 0) { const int t = lane; const float iv = pre.iv, lf = logsigmoid_f(pre.gf);
;         float bcum = lf;
; #pragma unroll
;         for (int o = 1; o < 64; o <<= 1) { const float v = __shfl_up(bcum, o); if (lane >= o) bcum += v; }
;         float pm = iv - bcum;
; #pragma unroll
;         for (int o = 1; o < 64; o <<= 1) { const float v = __shfl_up(pm, o); if (lane >= o) pm = fmaxf(pm, v); }
;         bc[t] = bcum; ig[t] = iv; ml[t] = bcum + pm; }
.LBB0_1377:
	s_bfe_u32 s24, s19, 0x70002
	s_and_b32 s0, s19, 0xfffffe00
	s_lshl_b32 s1, s24, 2
	s_and_b32 s23, s19, 3
	s_or_b32 s0, s1, s0
	s_or_b32 s0, s0, s23
	v_mov_b32_e32 v152, v0
	s_ashr_i32 s1, s0, 31
	s_lshl_b64 s[0:1], s[0:1], 17
	v_ashrrev_i32_e32 v56, 6, v152
	v_readlane_b32 s4, v252, 45
	v_and_b32_e32 v194, 63, v152
	v_readfirstlane_b32 s22, v56
	s_add_u32 s0, s4, s0
	v_readlane_b32 s4, v252, 46
	s_addc_u32 s1, s4, s1
	v_lshlrev_b32_e32 v154, 3, v194
	v_mov_b32_e32 v155, v2
	s_lshl_b32 s16, s22, 7
	v_lshl_add_u64 v[36:37], v[154:155], 1, s[0:1]
	s_lshl_b32 s0, s16, 1
	s_mov_b32 s1, 0
	v_lshl_add_u64 v[38:39], s[0:1], 3, v[36:37]
	s_add_i32 s0, s0, 0x800
	global_load_dwordx4 v[148:151], v[38:39], off
	global_load_dwordx4 v[144:147], v[38:39], off offset:1024
	v_lshl_add_u64 v[58:59], s[0:1], 3, v[36:37]
	s_add_i32 s0, s0, 0x800
	global_load_dwordx4 v[132:135], v[58:59], off
	global_load_dwordx4 v[140:143], v[58:59], off offset:1024
	v_lshl_add_u64 v[60:61], s[0:1], 3, v[36:37]
	s_add_i32 s0, s0, 0x800
	global_load_dwordx4 v[120:123], v[60:61], off
	global_load_dwordx4 v[136:139], v[60:61], off offset:1024
	v_lshl_add_u64 v[62:63], s[0:1], 3, v[36:37]
	s_add_i32 s0, s0, 0x800
	global_load_dwordx4 v[112:115], v[62:63], off
	global_load_dwordx4 v[128:131], v[62:63], off offset:1024
	v_lshl_add_u64 v[64:65], s[0:1], 3, v[36:37]
	s_add_i32 s0, s0, 0x800
	global_load_dwordx4 v[108:111], v[64:65], off
	global_load_dwordx4 v[124:127], v[64:65], off offset:1024
	v_lshl_add_u64 v[66:67], s[0:1], 3, v[36:37]
	s_add_i32 s0, s0, 0x800
	global_load_dwordx4 v[100:103], v[66:67], off
	global_load_dwordx4 v[116:119], v[66:67], off offset:1024
	v_lshl_add_u64 v[68:69], s[0:1], 3, v[36:37]
	s_add_i32 s0, s0, 0x800
	global_load_dwordx4 v[92:95], v[68:69], off
	global_load_dwordx4 v[104:107], v[68:69], off offset:1024
	v_lshl_add_u64 v[38:39], s[0:1], 3, v[36:37]
	global_load_dwordx4 v[88:91], v[38:39], off
	global_load_dwordx4 v[96:99], v[38:39], off offset:1024
	s_ashr_i32 s17, s16, 31
	s_cmp_lg_u32 s22, 0
	v_cmp_gt_u32_e32 vcc, 16, v194
	s_cbranch_scc1 .LBB0_1379
	s_waitcnt vmcnt(16)
	v_mul_f32_e64 v36, |v186|, s81
	v_exp_f32_e32 v36, v36
	v_max_f32_e32 v37, v186, v186
	v_min_f32_e32 v37, 0, v37
	v_add_f32_e32 v36, 1.0, v36
	v_cmp_gt_f32_e64 s[0:1], s75, v36
	s_nop 1
	v_cndmask_b32_e64 v38, 0, 32, s[0:1]
	v_ldexp_f32 v36, v36, v38
	v_log_f32_e32 v36, v36
	v_cndmask_b32_e64 v39, 0, v236, s[0:1]
	v_and_b32_e32 v38, 64, v235
	v_mul_f32_e32 v57, 0x3f317217, v36
	v_fma_f32 v57, v36, s15, -v57
	v_fmac_f32_e32 v57, 0x3377d1cf, v36
	v_fmac_f32_e32 v57, 0x3f317217, v36
	v_cmp_lt_f32_e64 s[0:1], |v36|, s78
	s_nop 1
	v_cndmask_b32_e64 v36, v36, v57, s[0:1]
	v_sub_f32_e32 v36, v36, v39
	v_sub_f32_e32 v36, v37, v36
	v_add_u32_e32 v37, -1, v235
	v_cmp_lt_i32_e64 s[0:1], v37, v38
	s_nop 1
	v_cndmask_b32_e64 v37, v37, v235, s[0:1]
	v_lshlrev_b32_e32 v37, 2, v37
	ds_bpermute_b32 v39, v37, v36
	v_cmp_eq_u32_e64 s[0:1], 0, v194
	s_waitcnt lgkmcnt(0)
	v_add_f32_e32 v39, v36, v39
	v_cndmask_b32_e64 v36, v39, v36, s[0:1]
	v_add_u32_e32 v39, -2, v235
	v_cmp_lt_i32_e64 s[4:5], v39, v38
	s_nop 1
	v_cndmask_b32_e64 v39, v39, v235, s[4:5]
	v_lshlrev_b32_e32 v39, 2, v39
	ds_bpermute_b32 v57, v39, v36
	v_cmp_gt_u32_e64 s[4:5], 2, v194
	s_waitcnt lgkmcnt(0)
	v_add_f32_e32 v57, v36, v57
	v_cndmask_b32_e64 v36, v57, v36, s[4:5]
	v_add_u32_e32 v57, -4, v235
	v_cmp_lt_i32_e64 s[6:7], v57, v38
	s_nop 1
	v_cndmask_b32_e64 v57, v57, v235, s[6:7]
	v_lshlrev_b32_e32 v57, 2, v57
	ds_bpermute_b32 v58, v57, v36
	v_cmp_gt_u32_e64 s[6:7], 4, v194
	s_waitcnt lgkmcnt(0)
	v_add_f32_e32 v58, v36, v58
	v_cndmask_b32_e64 v36, v58, v36, s[6:7]
	v_add_u32_e32 v58, -8, v235
	v_cmp_lt_i32_e64 s[8:9], v58, v38
	s_nop 1
	v_cndmask_b32_e64 v58, v58, v235, s[8:9]
	v_lshlrev_b32_e32 v58, 2, v58
	ds_bpermute_b32 v59, v58, v36
	v_cmp_gt_u32_e64 s[8:9], 8, v194
	s_waitcnt lgkmcnt(0)
	v_add_f32_e32 v59, v36, v59
	v_cndmask_b32_e64 v36, v59, v36, s[8:9]
	v_add_u32_e32 v59, -16, v235
	v_cmp_lt_i32_e64 s[10:11], v59, v38
	s_nop 1
	v_cndmask_b32_e64 v59, v59, v235, s[10:11]
	v_lshlrev_b32_e32 v59, 2, v59
	ds_bpermute_b32 v60, v59, v36
	s_waitcnt lgkmcnt(0)
	v_add_f32_e32 v60, v36, v60
	v_cndmask_b32_e32 v36, v60, v36, vcc
	v_subrev_u32_e32 v60, 32, v235
	v_cmp_lt_i32_e64 s[10:11], v60, v38
	s_nop 1
	v_cndmask_b32_e64 v38, v60, v235, s[10:11]
	v_lshlrev_b32_e32 v38, 2, v38
	ds_bpermute_b32 v60, v38, v36
	v_cmp_gt_u32_e64 s[10:11], 32, v194
	s_waitcnt lgkmcnt(0)
	v_add_f32_e32 v60, v36, v60
	v_cndmask_b32_e64 v36, v60, v36, s[10:11]
	v_sub_f32_e32 v60, v3, v36
	ds_bpermute_b32 v37, v37, v60
	s_waitcnt lgkmcnt(0)
	v_max_f32_e32 v37, v37, v37
	v_max_f32_e32 v37, v60, v37
	v_cndmask_b32_e64 v37, v37, v60, s[0:1]
	ds_bpermute_b32 v39, v39, v37
	s_waitcnt lgkmcnt(0)
	v_max_f32_e32 v39, v39, v39
	v_max_f32_e32 v39, v37, v39
	v_cndmask_b32_e64 v37, v39, v37, s[4:5]
	ds_bpermute_b32 v39, v57, v37
	v_lshl_add_u32 v57, v194, 2, 0
	s_waitcnt lgkmcnt(0)
	v_max_f32_e32 v39, v39, v39
	v_max_f32_e32 v39, v37, v39
	v_cndmask_b32_e64 v37, v39, v37, s[6:7]
	ds_bpermute_b32 v39, v58, v37
	v_add_u32_e32 v58, 0x18c00, v57
	s_waitcnt lgkmcnt(0)
	v_max_f32_e32 v39, v39, v39
	v_max_f32_e32 v39, v37, v39
	v_cndmask_b32_e64 v37, v39, v37, s[8:9]
	ds_bpermute_b32 v39, v59, v37
	s_waitcnt lgkmcnt(0)
	v_max_f32_e32 v39, v39, v39
	v_max_f32_e32 v39, v37, v39
	v_cndmask_b32_e32 v37, v39, v37, vcc
	ds_bpermute_b32 v38, v38, v37
	v_add_u32_e32 v39, 0x18d00, v57
	ds_write_b32 v39, v3
	ds_write_b32 v58, v36
	v_max_f32_e32 v39, v37, v37
	s_waitcnt lgkmcnt(2)
	v_max_f32_e32 v38, v38, v38
	v_max_f32_e32 v38, v39, v38
	v_cndmask_b32_e64 v37, v38, v37, s[10:11]
	v_add_f32_e32 v36, v36, v37
	v_add_u32_e32 v37, 0x18e00, v57
	ds_write_b32 v37, v36
; #define LAS __attribute__((address_space(3)))
; __device__ __forceinline__ float bflo(unsigned w) { return __uint_as_float(w << 16); }
; __device__ __forceinline__ float bfhi(unsigned w) { return __uint_as_float(w & 0xffff0000u); }
; __device__ __forceinline__ void mlstm_out_unit(const KP& p, int j, int b, int n, int h, LAS unsigned char* lds, TilesML& pre, bool has_next, int b2, int n2, int h2) {
;     ...
;     { LAS u32x4* dq = (LAS u32x4*)(Qs + t_ * 264 + sg * 32); LAS u32x4* dk = (LAS u32x4*)(Ks + t_ * 264 + sg * 32); LAS u32x4* dv = (LAS u32x4*)(Vs + t_ * 264 + sg * 32);
; #pragma unroll
;       for (int c = 0; c < 4; ++c) { dq[c] = pre.q[c]; dk[c] = pre.k[c]; dv[c] = pre.v[c]; }
;       if (tid < 256) nvec[tid] = pre.nv; }
;     const float m = pre.m;
;     __syncthreads();
;     { const int t = tid & 63, part = tid >> 6; float s = 0.f;
; #pragma unroll
;       for (int dd = 0; dd < 32; dd += 2) { const unsigned w = *(const LAS unsigned*)(Qs + t * 264 + part * 32 + dd); s += bflo(w) * nvec[part * 32 + dd] + bfhi(w) * nvec[part * 32 + dd + 1]; }
;       qnp[part * 64 + t] = s; }
;     { const int tt = wave >> 1, stb = (wave & 1) * 2; f32x4 acc[2] = {F4ZERO, F4ZERO};
;       if (stb <= tt) {
.LBB0_1379:
	v_lshlrev_b32_e32 v190, 5, v152
	v_ashrrev_i32_e32 v188, 3, v152
	v_and_b32_e32 v189, 0xe0, v190
	v_mul_lo_u32 v36, v188, s79
	v_lshlrev_b32_e32 v37, 1, v189
	s_movk_i32 s0, 0x100
	v_add3_u32 v38, 0, v36, v37
	s_add_i32 s10, 0, 0x10800
	v_cmp_gt_i32_e64 s[4:5], s0, v152
	v_lshl_add_u32 v57, v152, 2, 0
	v_add3_u32 v36, s10, v36, v37
	s_waitcnt vmcnt(16)
	ds_write_b128 v38, v[16:19]
	ds_write_b128 v38, v[32:35] offset:33792
	ds_write_b128 v36, v[52:55]
	ds_write_b128 v38, v[12:15] offset:16
	ds_write_b128 v38, v[28:31] offset:33808
	ds_write_b128 v36, v[48:51] offset:16
	ds_write_b128 v38, v[8:11] offset:32
	ds_write_b128 v38, v[24:27] offset:33824
	ds_write_b128 v36, v[44:47] offset:32
	ds_write_b128 v38, v[4:7] offset:48
	ds_write_b128 v38, v[20:23] offset:33840
	ds_write_b128 v36, v[40:43] offset:48
	s_and_saveexec_b64 s[0:1], s[4:5]
	v_add_u32_e32 v36, 0x19f00, v57
	ds_write_b32 v36, v187
	s_or_b64 exec, exec, s[0:1]
	v_mul_u32_u24_e32 v36, 0x210, v194
	v_lshlrev_b32_e32 v37, 6, v56
	v_add3_u32 v36, 0, v36, v37
	s_waitcnt lgkmcnt(0)
	s_barrier
	ds_read_b128 v[58:61], v36
	v_lshl_add_u32 v37, v56, 7, 0
	v_add_u32_e32 v56, 0x19f00, v37
	ds_read_b128 v[62:65], v36 offset:16
	ds_read_b128 v[66:69], v36 offset:32
	ds_read_b128 v[70:73], v36 offset:48
	ds_read_b128 v[74:77], v56
	ds_read_b128 v[78:81], v56 offset:16
	ds_read_b128 v[82:85], v56 offset:32
	ds_read_b128 v[156:159], v56 offset:48
	s_waitcnt lgkmcnt(7)
	v_and_b32_e32 v37, 0xffff0000, v58
	v_lshlrev_b32_e32 v36, 16, v58
	s_waitcnt lgkmcnt(3)
	v_mul_f32_e32 v37, v75, v37
	v_fmac_f32_e32 v37, v74, v36
	v_and_b32_e32 v38, 0xffff0000, v59
	v_add_f32_e32 v36, 0, v37
	v_lshlrev_b32_e32 v37, 16, v59
	v_mul_f32_e32 v38, v77, v38
	v_fmac_f32_e32 v38, v76, v37
	v_add_f32_e32 v36, v36, v38
	v_and_b32_e32 v38, 0xffff0000, v60
	v_lshlrev_b32_e32 v37, 16, v60
	s_waitcnt lgkmcnt(2)
	v_mul_f32_e32 v38, v79, v38
	v_fmac_f32_e32 v38, v78, v37
	v_add_f32_e32 v36, v36, v38
	v_and_b32_e32 v38, 0xffff0000, v61
	v_lshlrev_b32_e32 v37, 16, v61
	v_mul_f32_e32 v38, v81, v38
	v_fmac_f32_e32 v38, v80, v37
	v_add_f32_e32 v60, v36, v38
	s_waitcnt lgkmcnt(1)
	v_mov_b32_e32 v36, v83
	v_lshlrev_b32_e32 v58, 16, v62
	v_and_b32_e32 v59, 0xffff0000, v63
	v_mov_b32_e32 v83, v85
	v_mov_b32_e32 v37, v84
	v_and_b32_e32 v38, 0xffff0000, v62
	v_lshlrev_b32_e32 v39, 16, v63
	v_pk_mul_f32 v[58:59], v[82:83], v[58:59]
	s_lshl_b32 s0, s22, 1
	v_pk_fma_f32 v[36:37], v[36:37], v[38:39], v[58:59]
	v_lshlrev_b32_e32 v58, 16, v64
	v_add_f32_e32 v36, v60, v36
	v_add_f32_e32 v74, v36, v37
	s_waitcnt lgkmcnt(0)
	v_mov_b32_e32 v36, v157
	v_and_b32_e32 v59, 0xffff0000, v65
	v_mov_b32_e32 v157, v159
	v_pk_mul_f32 v[62:63], v[156:157], v[58:59]
	ds_read_b128 v[58:61], v56 offset:64
	v_mov_b32_e32 v37, v158
	v_and_b32_e32 v38, 0xffff0000, v64
	v_lshlrev_b32_e32 v39, 16, v65
	v_pk_fma_f32 v[36:37], v[36:37], v[38:39], v[62:63]
	ds_read_b128 v[62:65], v56 offset:80
	v_add_f32_e32 v36, v74, v36
	v_add_f32_e32 v74, v36, v37
	s_waitcnt lgkmcnt(1)
	v_mov_b32_e32 v36, v59
	v_and_b32_e32 v38, 0xffff0000, v66
	v_lshlrev_b32_e32 v39, 16, v67
	v_lshlrev_b32_e32 v66, 16, v66
	v_and_b32_e32 v67, 0xffff0000, v67
	v_mov_b32_e32 v59, v61
	v_mov_b32_e32 v37, v60
	v_pk_mul_f32 v[58:59], v[58:59], v[66:67]
	v_and_b32_e32 v67, 0xffff0000, v71
	v_pk_fma_f32 v[36:37], v[36:37], v[38:39], v[58:59]
	v_lshlrev_b32_e32 v58, 16, v68
	v_add_f32_e32 v36, v74, v36
	v_add_f32_e32 v66, v36, v37
	s_waitcnt lgkmcnt(0)
	v_mov_b32_e32 v36, v63
	v_and_b32_e32 v59, 0xffff0000, v69
	v_mov_b32_e32 v63, v65
	v_pk_mul_f32 v[62:63], v[62:63], v[58:59]
	ds_read_b128 v[58:61], v56 offset:96
	v_mov_b32_e32 v37, v64
	v_and_b32_e32 v38, 0xffff0000, v68
	v_lshlrev_b32_e32 v39, 16, v69
	v_pk_fma_f32 v[36:37], v[36:37], v[38:39], v[62:63]
	ds_read_b128 v[62:65], v56 offset:112
	v_add_f32_e32 v36, v66, v36
	v_add_f32_e32 v68, v36, v37
	s_waitcnt lgkmcnt(1)
	v_mov_b32_e32 v36, v59
	v_lshlrev_b32_e32 v66, 16, v70
	v_mov_b32_e32 v59, v61
	v_mov_b32_e32 v37, v60
	v_and_b32_e32 v38, 0xffff0000, v70
	v_lshlrev_b32_e32 v39, 16, v71
	v_pk_mul_f32 v[58:59], v[58:59], v[66:67]
	s_ashr_i32 s6, s22, 1
	v_pk_fma_f32 v[36:37], v[36:37], v[38:39], v[58:59]
	v_lshlrev_b32_e32 v58, 16, v72
	v_add_f32_e32 v36, v68, v36
	v_add_f32_e32 v56, v36, v37
	s_waitcnt lgkmcnt(0)
	v_mov_b32_e32 v36, v63
	v_and_b32_e32 v59, 0xffff0000, v73
	v_mov_b32_e32 v63, v65
	v_mov_b32_e32 v37, v64
	v_and_b32_e32 v38, 0xffff0000, v72
	v_lshlrev_b32_e32 v39, 16, v73
	v_pk_mul_f32 v[58:59], v[62:63], v[58:59]
	s_and_b32 s8, s0, 2
	v_pk_fma_f32 v[36:37], v[36:37], v[38:39], v[58:59]
	s_mov_b64 s[0:1], -1
	v_add_f32_e32 v36, v56, v36
	v_add_f32_e32 v36, v36, v37
	v_add_u32_e32 v37, 0x18f00, v57
	s_cmp_le_i32 s8, s6
	v_and_b32_e32 v192, 48, v152
	v_and_b32_e32 v64, 15, v152
	ds_write_b32 v37, v36
	s_cbranch_scc0 .LBB0_1383
; #define MFMA16(a, b, c) __builtin_amdgcn_mfma_f32_16x16x32_bf16((a), (b), (c), 0, 0, 0)
; __device__ __forceinline__ void mlstm_out_unit(const KP& p, int j, int b, int n, int h, LAS unsigned char* lds, TilesML& pre, bool has_next, int b2, int n2, int h2) {
;     ...
;     { const int tt = wave >> 1, stb = (wave & 1) * 2; f32x4 acc[2] = {F4ZERO, F4ZERO};
;       if (stb <= tt) {
; #pragma unroll
;           for (int ks = 0; ks < 8; ++ks) { const bf16x8 a = lds_frag(Qs, 264, tt * 16, ks * 32, lane);
; #pragma unroll
;               for (int s2 = 0; s2 < 2; ++s2) acc[s2] = MFMA16(a, lds_frag(Ks, 264, (stb + s2) * 16, ks * 32, lane), acc[s2]); } }
	s_lshl_b32 s7, s6, 4
	v_and_b32_e32 v193, 15, v152
	v_or_b32_e32 v37, s7, v193
	v_add_u32_e32 v36, 0, v192
	v_mad_u64_u32 v[38:39], s[0:1], v37, s79, v[36:37]
	ds_read_b128 v[56:59], v38
	v_lshl_or_b32 v67, s8, 4, v193
	v_mad_u32_u24 v36, v67, s79, v36
	ds_read_b128 v[60:63], v36 offset:33792
	ds_read_b128 v[68:71], v36 offset:42240
	s_mov_b64 s[0:1], 0
	s_waitcnt lgkmcnt(1)
	v_mfma_f32_16x16x32_bf16 v[60:63], v[56:59], v[60:63], 0
	v_mov_b32_e32 v65, s7
	s_waitcnt lgkmcnt(0)
	v_mfma_f32_16x16x32_bf16 v[56:59], v[56:59], v[68:71], 0
	ds_read_b128 v[68:71], v38 offset:64
	ds_read_b128 v[72:75], v36 offset:33856
	s_waitcnt lgkmcnt(0)
	v_mfma_f32_16x16x32_bf16 v[60:63], v[68:71], v[72:75], v[60:63]
	ds_read_b128 v[72:75], v36 offset:42304
	s_waitcnt lgkmcnt(0)
	v_mfma_f32_16x16x32_bf16 v[56:59], v[68:71], v[72:75], v[56:59]
	ds_read_b128 v[68:71], v38 offset:128
	ds_read_b128 v[72:75], v36 offset:33920
	s_waitcnt lgkmcnt(0)
	v_mfma_f32_16x16x32_bf16 v[60:63], v[68:71], v[72:75], v[60:63]
	ds_read_b128 v[72:75], v36 offset:42368
	s_waitcnt lgkmcnt(0)
	v_mfma_f32_16x16x32_bf16 v[56:59], v[68:71], v[72:75], v[56:59]
	ds_read_b128 v[68:71], v38 offset:192
	ds_read_b128 v[72:75], v36 offset:33984
	s_waitcnt lgkmcnt(0)
	v_mfma_f32_16x16x32_bf16 v[60:63], v[68:71], v[72:75], v[60:63]
	ds_read_b128 v[72:75], v36 offset:42432
	s_waitcnt lgkmcnt(0)
	v_mfma_f32_16x16x32_bf16 v[56:59], v[68:71], v[72:75], v[56:59]
	ds_read_b128 v[68:71], v38 offset:256
	ds_read_b128 v[72:75], v36 offset:34048
	s_waitcnt lgkmcnt(0)
	v_mfma_f32_16x16x32_bf16 v[60:63], v[68:71], v[72:75], v[60:63]
	ds_read_b128 v[72:75], v36 offset:42496
	s_waitcnt lgkmcnt(0)
	v_mfma_f32_16x16x32_bf16 v[56:59], v[68:71], v[72:75], v[56:59]
	ds_read_b128 v[68:71], v38 offset:320
	ds_read_b128 v[72:75], v36 offset:34112
	s_waitcnt lgkmcnt(0)
	v_mfma_f32_16x16x32_bf16 v[60:63], v[68:71], v[72:75], v[60:63]
	ds_read_b128 v[72:75], v36 offset:42560
	s_waitcnt lgkmcnt(0)
	v_mfma_f32_16x16x32_bf16 v[56:59], v[68:71], v[72:75], v[56:59]
	ds_read_b128 v[68:71], v38 offset:384
	ds_read_b128 v[72:75], v36 offset:34176
	s_waitcnt lgkmcnt(0)
	v_mfma_f32_16x16x32_bf16 v[60:63], v[68:71], v[72:75], v[60:63]
	ds_read_b128 v[72:75], v36 offset:42624
	s_waitcnt lgkmcnt(0)
	v_mfma_f32_16x16x32_bf16 v[56:59], v[68:71], v[72:75], v[56:59]
	ds_read_b128 v[68:71], v38 offset:448
	ds_read_b128 v[72:75], v36 offset:34240
	s_waitcnt lgkmcnt(0)
	v_mfma_f32_16x16x32_bf16 v[60:63], v[68:71], v[72:75], v[60:63]
	ds_read_b128 v[72:75], v36 offset:42688
	s_waitcnt lgkmcnt(0)
	v_mfma_f32_16x16x32_bf16 v[56:59], v[68:71], v[72:75], v[56:59]
